# prologue phase modulation-table GEMV: weight row loads issued three iterations ahead (4 register sets) instead of a full drain per iteration
# speedup vs baseline: 1.0060x; 1.0060x over previous
.LBB0_409:
	v_mov_b64_e32 v[148:149], v[10:11]
	v_add_co_u32_e64 v150, s[0:1], s11, v148
	s_nop 1
	v_addc_co_u32_e64 v151, s[0:1], -1, v149, s[0:1]
	v_add_co_u32_e64 v152, s[0:1], s12, v148
	s_nop 1
	v_addc_co_u32_e64 v153, s[0:1], -1, v149, s[0:1]
	v_add_co_u32_e64 v154, s[0:1], s13, v148
	global_load_dword v100, v[150:151], off
	global_load_dword v102, v[152:153], off
	v_addc_co_u32_e64 v155, s[0:1], -1, v149, s[0:1]
	global_load_dword v106, v[148:149], off
	global_load_dword v104, v[154:155], off
	v_lshl_add_u64 v[148:149], v[148:149], 0, s[2:3]
	v_add_co_u32_e64 v150, s[0:1], s11, v148
	s_nop 1
	v_addc_co_u32_e64 v151, s[0:1], -1, v149, s[0:1]
	v_add_co_u32_e64 v152, s[0:1], s12, v148
	s_nop 1
	v_addc_co_u32_e64 v153, s[0:1], -1, v149, s[0:1]
	v_add_co_u32_e64 v154, s[0:1], s13, v148
	global_load_dword v124, v[150:151], off
	global_load_dword v126, v[152:153], off
	v_addc_co_u32_e64 v155, s[0:1], -1, v149, s[0:1]
	global_load_dword v130, v[148:149], off
	global_load_dword v128, v[154:155], off
	v_lshl_add_u64 v[148:149], v[148:149], 0, s[2:3]
	v_add_co_u32_e64 v150, s[0:1], s11, v148
	s_nop 1
	v_addc_co_u32_e64 v151, s[0:1], -1, v149, s[0:1]
	v_add_co_u32_e64 v152, s[0:1], s12, v148
	s_nop 1
	v_addc_co_u32_e64 v153, s[0:1], -1, v149, s[0:1]
	v_add_co_u32_e64 v154, s[0:1], s13, v148
	global_load_dword v132, v[150:151], off
	global_load_dword v134, v[152:153], off
	v_addc_co_u32_e64 v155, s[0:1], -1, v149, s[0:1]
	global_load_dword v138, v[148:149], off
	global_load_dword v136, v[154:155], off
	v_lshl_add_u64 v[148:149], v[148:149], 0, s[2:3]
.Lmodp_loop:
	v_add_u32_e32 v31, s6, v3
	s_add_i32 s6, s6, 16
	v_add_co_u32_e64 v150, s[0:1], s11, v148
	s_nop 1
	v_addc_co_u32_e64 v151, s[0:1], -1, v149, s[0:1]
	v_add_co_u32_e64 v152, s[0:1], s12, v148
	s_nop 1
	v_addc_co_u32_e64 v153, s[0:1], -1, v149, s[0:1]
	v_add_co_u32_e64 v154, s[0:1], s13, v148
	global_load_dword v140, v[150:151], off
	global_load_dword v142, v[152:153], off
	v_addc_co_u32_e64 v155, s[0:1], -1, v149, s[0:1]
	global_load_dword v146, v[148:149], off
	global_load_dword v144, v[154:155], off
	v_lshl_add_u64 v[148:149], v[148:149], 0, s[2:3]
	ds_read_b128 v[32:35], v31
	ds_read_b128 v[36:39], v31 offset:4096
	ds_read_b128 v[40:43], v31 offset:8192
	ds_read_b128 v[44:47], v31 offset:12288
	ds_read_b128 v[48:51], v31 offset:16384
	ds_read_b128 v[52:55], v31 offset:20480
	ds_read_b128 v[56:59], v31 offset:24576
	ds_read_b128 v[60:63], v31 offset:28672
	ds_read_b128 v[64:67], v31 offset:32768
	ds_read_b128 v[68:71], v31 offset:36864
	ds_read_b128 v[72:75], v31 offset:40960
	ds_read_b128 v[76:79], v31 offset:45056
	ds_read_b128 v[80:83], v31 offset:49152
	ds_read_b128 v[84:87], v31 offset:53248
	ds_read_b128 v[88:91], v31 offset:57344
	ds_read_b128 v[92:95], v31 offset:61440
	v_add_u32_e32 v31, 0x10000, v31
	ds_read_b128 v[96:99], v31
	s_waitcnt lgkmcnt(14)
	v_mov_b32_e32 v108, v32
	v_mov_b32_e32 v109, v36
	v_mov_b32_e32 v110, v40
	s_waitcnt lgkmcnt(13)
	v_mov_b32_e32 v111, v44
	s_waitcnt lgkmcnt(12)
	v_mov_b32_e32 v112, v48
	s_waitcnt lgkmcnt(11)
	v_mov_b32_e32 v113, v52
	s_waitcnt lgkmcnt(10)
	v_mov_b32_e32 v114, v56
	s_waitcnt lgkmcnt(9)
	v_mov_b32_e32 v115, v60
	s_waitcnt lgkmcnt(8)
	v_mov_b32_e32 v116, v64
	s_waitcnt lgkmcnt(7)
	v_mov_b32_e32 v117, v68
	s_waitcnt lgkmcnt(6)
	v_mov_b32_e32 v118, v72
	s_waitcnt lgkmcnt(5)
	v_mov_b32_e32 v119, v76
	s_waitcnt lgkmcnt(4)
	v_mov_b32_e32 v120, v80
	s_waitcnt lgkmcnt(3)
	v_mov_b32_e32 v121, v84
	s_waitcnt lgkmcnt(2)
	v_mov_b32_e32 v122, v88
	s_waitcnt lgkmcnt(1)
	v_mov_b32_e32 v123, v92
	v_mov_b32_e32 v36, v33
	v_mov_b32_e32 v44, v41
	v_mov_b32_e32 v52, v49
	v_mov_b32_e32 v60, v57
	v_mov_b32_e32 v68, v65
	v_mov_b32_e32 v76, v73
	v_mov_b32_e32 v84, v81
	v_mov_b32_e32 v92, v89
	v_mov_b32_e32 v32, v34
	v_mov_b32_e32 v33, v38
	v_mov_b32_e32 v40, v42
	v_mov_b32_e32 v41, v46
	v_mov_b32_e32 v48, v50
	v_mov_b32_e32 v49, v54
	v_mov_b32_e32 v56, v58
	v_mov_b32_e32 v57, v62
	v_mov_b32_e32 v64, v66
	v_mov_b32_e32 v65, v70
	v_mov_b32_e32 v72, v74
	v_mov_b32_e32 v73, v78
	v_mov_b32_e32 v38, v35
	v_mov_b32_e32 v34, v82
	v_mov_b32_e32 v35, v86
	v_mov_b32_e32 v80, v90
	v_mov_b32_e32 v81, v94
	v_mov_b32_e32 v46, v43
	v_mov_b32_e32 v54, v51
	v_mov_b32_e32 v62, v59
	v_mov_b32_e32 v70, v67
	v_mov_b32_e32 v78, v75
	v_mov_b32_e32 v86, v83
	v_mov_b32_e32 v94, v91
	s_waitcnt vmcnt(12)
	v_pk_fma_f32 v[12:13], v[100:101], v[108:109], v[12:13] op_sel_hi:[0,1,1]
	v_pk_fma_f32 v[14:15], v[100:101], v[110:111], v[14:15] op_sel_hi:[0,1,1]
	v_pk_fma_f32 v[16:17], v[100:101], v[112:113], v[16:17] op_sel_hi:[0,1,1]
	v_pk_fma_f32 v[18:19], v[100:101], v[114:115], v[18:19] op_sel_hi:[0,1,1]
	v_pk_fma_f32 v[20:21], v[100:101], v[116:117], v[20:21] op_sel_hi:[0,1,1]
	v_pk_fma_f32 v[22:23], v[100:101], v[118:119], v[22:23] op_sel_hi:[0,1,1]
	v_pk_fma_f32 v[24:25], v[100:101], v[120:121], v[24:25] op_sel_hi:[0,1,1]
	v_pk_fma_f32 v[26:27], v[100:101], v[122:123], v[26:27] op_sel_hi:[0,1,1]
	s_waitcnt lgkmcnt(0)
	v_fmac_f32_e32 v30, v100, v96
	v_pk_fma_f32 v[12:13], v[102:103], v[36:37], v[12:13] op_sel_hi:[0,1,1]
	v_pk_fma_f32 v[14:15], v[102:103], v[44:45], v[14:15] op_sel_hi:[0,1,1]
	v_pk_fma_f32 v[16:17], v[102:103], v[52:53], v[16:17] op_sel_hi:[0,1,1]
	v_pk_fma_f32 v[18:19], v[102:103], v[60:61], v[18:19] op_sel_hi:[0,1,1]
	v_pk_fma_f32 v[20:21], v[102:103], v[68:69], v[20:21] op_sel_hi:[0,1,1]
	v_pk_fma_f32 v[22:23], v[102:103], v[76:77], v[22:23] op_sel_hi:[0,1,1]
	v_pk_fma_f32 v[24:25], v[102:103], v[84:85], v[24:25] op_sel_hi:[0,1,1]
	v_pk_fma_f32 v[26:27], v[102:103], v[92:93], v[26:27] op_sel_hi:[0,1,1]
	v_fmac_f32_e32 v30, v102, v97
	v_pk_fma_f32 v[12:13], v[104:105], v[32:33], v[12:13] op_sel_hi:[0,1,1]
	v_pk_fma_f32 v[14:15], v[104:105], v[40:41], v[14:15] op_sel_hi:[0,1,1]
	v_pk_fma_f32 v[16:17], v[104:105], v[48:49], v[16:17] op_sel_hi:[0,1,1]
	v_pk_fma_f32 v[18:19], v[104:105], v[56:57], v[18:19] op_sel_hi:[0,1,1]
	v_pk_fma_f32 v[20:21], v[104:105], v[64:65], v[20:21] op_sel_hi:[0,1,1]
	v_pk_fma_f32 v[22:23], v[104:105], v[72:73], v[22:23] op_sel_hi:[0,1,1]
	v_pk_fma_f32 v[24:25], v[104:105], v[34:35], v[24:25] op_sel_hi:[0,1,1]
	v_pk_fma_f32 v[26:27], v[104:105], v[80:81], v[26:27] op_sel_hi:[0,1,1]
	v_fmac_f32_e32 v30, v104, v98
	v_pk_fma_f32 v[12:13], v[106:107], v[38:39], v[12:13] op_sel_hi:[0,1,1]
	v_pk_fma_f32 v[14:15], v[106:107], v[46:47], v[14:15] op_sel_hi:[0,1,1]
	v_pk_fma_f32 v[16:17], v[106:107], v[54:55], v[16:17] op_sel_hi:[0,1,1]
	v_pk_fma_f32 v[18:19], v[106:107], v[62:63], v[18:19] op_sel_hi:[0,1,1]
	v_pk_fma_f32 v[20:21], v[106:107], v[70:71], v[20:21] op_sel_hi:[0,1,1]
	v_pk_fma_f32 v[22:23], v[106:107], v[78:79], v[22:23] op_sel_hi:[0,1,1]
	v_pk_fma_f32 v[24:25], v[106:107], v[86:87], v[24:25] op_sel_hi:[0,1,1]
	v_pk_fma_f32 v[26:27], v[106:107], v[94:95], v[26:27] op_sel_hi:[0,1,1]
	v_fmac_f32_e32 v30, v106, v99
	v_add_u32_e32 v31, s6, v3
	s_add_i32 s6, s6, 16
	v_add_co_u32_e64 v150, s[0:1], s11, v148
	s_nop 1
	v_addc_co_u32_e64 v151, s[0:1], -1, v149, s[0:1]
	v_add_co_u32_e64 v152, s[0:1], s12, v148
	s_nop 1
	v_addc_co_u32_e64 v153, s[0:1], -1, v149, s[0:1]
	v_add_co_u32_e64 v154, s[0:1], s13, v148
	global_load_dword v100, v[150:151], off
	global_load_dword v102, v[152:153], off
	v_addc_co_u32_e64 v155, s[0:1], -1, v149, s[0:1]
	global_load_dword v106, v[148:149], off
	global_load_dword v104, v[154:155], off
	v_lshl_add_u64 v[148:149], v[148:149], 0, s[2:3]
	ds_read_b128 v[32:35], v31
	ds_read_b128 v[36:39], v31 offset:4096
	ds_read_b128 v[40:43], v31 offset:8192
	ds_read_b128 v[44:47], v31 offset:12288
	ds_read_b128 v[48:51], v31 offset:16384
	ds_read_b128 v[52:55], v31 offset:20480
	ds_read_b128 v[56:59], v31 offset:24576
	ds_read_b128 v[60:63], v31 offset:28672
	ds_read_b128 v[64:67], v31 offset:32768
	ds_read_b128 v[68:71], v31 offset:36864
	ds_read_b128 v[72:75], v31 offset:40960
	ds_read_b128 v[76:79], v31 offset:45056
	ds_read_b128 v[80:83], v31 offset:49152
	ds_read_b128 v[84:87], v31 offset:53248
	ds_read_b128 v[88:91], v31 offset:57344
	ds_read_b128 v[92:95], v31 offset:61440
	v_add_u32_e32 v31, 0x10000, v31
	ds_read_b128 v[96:99], v31
	s_waitcnt lgkmcnt(14)
	v_mov_b32_e32 v108, v32
	v_mov_b32_e32 v109, v36
	v_mov_b32_e32 v110, v40
	s_waitcnt lgkmcnt(13)
	v_mov_b32_e32 v111, v44
	s_waitcnt lgkmcnt(12)
	v_mov_b32_e32 v112, v48
	s_waitcnt lgkmcnt(11)
	v_mov_b32_e32 v113, v52
	s_waitcnt lgkmcnt(10)
	v_mov_b32_e32 v114, v56
	s_waitcnt lgkmcnt(9)
	v_mov_b32_e32 v115, v60
	s_waitcnt lgkmcnt(8)
	v_mov_b32_e32 v116, v64
	s_waitcnt lgkmcnt(7)
	v_mov_b32_e32 v117, v68
	s_waitcnt lgkmcnt(6)
	v_mov_b32_e32 v118, v72
	s_waitcnt lgkmcnt(5)
	v_mov_b32_e32 v119, v76
	s_waitcnt lgkmcnt(4)
	v_mov_b32_e32 v120, v80
	s_waitcnt lgkmcnt(3)
	v_mov_b32_e32 v121, v84
	s_waitcnt lgkmcnt(2)
	v_mov_b32_e32 v122, v88
	s_waitcnt lgkmcnt(1)
	v_mov_b32_e32 v123, v92
	v_mov_b32_e32 v36, v33
	v_mov_b32_e32 v44, v41
	v_mov_b32_e32 v52, v49
	v_mov_b32_e32 v60, v57
	v_mov_b32_e32 v68, v65
	v_mov_b32_e32 v76, v73
	v_mov_b32_e32 v84, v81
	v_mov_b32_e32 v92, v89
	v_mov_b32_e32 v32, v34
	v_mov_b32_e32 v33, v38
	v_mov_b32_e32 v40, v42
	v_mov_b32_e32 v41, v46
	v_mov_b32_e32 v48, v50
	v_mov_b32_e32 v49, v54
	v_mov_b32_e32 v56, v58
	v_mov_b32_e32 v57, v62
	v_mov_b32_e32 v64, v66
	v_mov_b32_e32 v65, v70
	v_mov_b32_e32 v72, v74
	v_mov_b32_e32 v73, v78
	v_mov_b32_e32 v38, v35
	v_mov_b32_e32 v34, v82
	v_mov_b32_e32 v35, v86
	v_mov_b32_e32 v80, v90
	v_mov_b32_e32 v81, v94
	v_mov_b32_e32 v46, v43
	v_mov_b32_e32 v54, v51
	v_mov_b32_e32 v62, v59
	v_mov_b32_e32 v70, v67
	v_mov_b32_e32 v78, v75
	v_mov_b32_e32 v86, v83
	v_mov_b32_e32 v94, v91
	s_waitcnt vmcnt(12)
	v_pk_fma_f32 v[12:13], v[124:125], v[108:109], v[12:13] op_sel_hi:[0,1,1]
	v_pk_fma_f32 v[14:15], v[124:125], v[110:111], v[14:15] op_sel_hi:[0,1,1]
	v_pk_fma_f32 v[16:17], v[124:125], v[112:113], v[16:17] op_sel_hi:[0,1,1]
	v_pk_fma_f32 v[18:19], v[124:125], v[114:115], v[18:19] op_sel_hi:[0,1,1]
	v_pk_fma_f32 v[20:21], v[124:125], v[116:117], v[20:21] op_sel_hi:[0,1,1]
	v_pk_fma_f32 v[22:23], v[124:125], v[118:119], v[22:23] op_sel_hi:[0,1,1]
	v_pk_fma_f32 v[24:25], v[124:125], v[120:121], v[24:25] op_sel_hi:[0,1,1]
	v_pk_fma_f32 v[26:27], v[124:125], v[122:123], v[26:27] op_sel_hi:[0,1,1]
	s_waitcnt lgkmcnt(0)
	v_fmac_f32_e32 v30, v124, v96
	v_pk_fma_f32 v[12:13], v[126:127], v[36:37], v[12:13] op_sel_hi:[0,1,1]
	v_pk_fma_f32 v[14:15], v[126:127], v[44:45], v[14:15] op_sel_hi:[0,1,1]
	v_pk_fma_f32 v[16:17], v[126:127], v[52:53], v[16:17] op_sel_hi:[0,1,1]
	v_pk_fma_f32 v[18:19], v[126:127], v[60:61], v[18:19] op_sel_hi:[0,1,1]
	v_pk_fma_f32 v[20:21], v[126:127], v[68:69], v[20:21] op_sel_hi:[0,1,1]
	v_pk_fma_f32 v[22:23], v[126:127], v[76:77], v[22:23] op_sel_hi:[0,1,1]
	v_pk_fma_f32 v[24:25], v[126:127], v[84:85], v[24:25] op_sel_hi:[0,1,1]
	v_pk_fma_f32 v[26:27], v[126:127], v[92:93], v[26:27] op_sel_hi:[0,1,1]
	v_fmac_f32_e32 v30, v126, v97
	v_pk_fma_f32 v[12:13], v[128:129], v[32:33], v[12:13] op_sel_hi:[0,1,1]
	v_pk_fma_f32 v[14:15], v[128:129], v[40:41], v[14:15] op_sel_hi:[0,1,1]
	v_pk_fma_f32 v[16:17], v[128:129], v[48:49], v[16:17] op_sel_hi:[0,1,1]
	v_pk_fma_f32 v[18:19], v[128:129], v[56:57], v[18:19] op_sel_hi:[0,1,1]
	v_pk_fma_f32 v[20:21], v[128:129], v[64:65], v[20:21] op_sel_hi:[0,1,1]
	v_pk_fma_f32 v[22:23], v[128:129], v[72:73], v[22:23] op_sel_hi:[0,1,1]
	v_pk_fma_f32 v[24:25], v[128:129], v[34:35], v[24:25] op_sel_hi:[0,1,1]
	v_pk_fma_f32 v[26:27], v[128:129], v[80:81], v[26:27] op_sel_hi:[0,1,1]
	v_fmac_f32_e32 v30, v128, v98
	v_pk_fma_f32 v[12:13], v[130:131], v[38:39], v[12:13] op_sel_hi:[0,1,1]
	v_pk_fma_f32 v[14:15], v[130:131], v[46:47], v[14:15] op_sel_hi:[0,1,1]
	v_pk_fma_f32 v[16:17], v[130:131], v[54:55], v[16:17] op_sel_hi:[0,1,1]
	v_pk_fma_f32 v[18:19], v[130:131], v[62:63], v[18:19] op_sel_hi:[0,1,1]
	v_pk_fma_f32 v[20:21], v[130:131], v[70:71], v[20:21] op_sel_hi:[0,1,1]
	v_pk_fma_f32 v[22:23], v[130:131], v[78:79], v[22:23] op_sel_hi:[0,1,1]
	v_pk_fma_f32 v[24:25], v[130:131], v[86:87], v[24:25] op_sel_hi:[0,1,1]
	v_pk_fma_f32 v[26:27], v[130:131], v[94:95], v[26:27] op_sel_hi:[0,1,1]
	v_fmac_f32_e32 v30, v130, v99
	v_add_u32_e32 v31, s6, v3
	s_add_i32 s6, s6, 16
	v_add_co_u32_e64 v150, s[0:1], s11, v148
	s_nop 1
	v_addc_co_u32_e64 v151, s[0:1], -1, v149, s[0:1]
	v_add_co_u32_e64 v152, s[0:1], s12, v148
	s_nop 1
	v_addc_co_u32_e64 v153, s[0:1], -1, v149, s[0:1]
	v_add_co_u32_e64 v154, s[0:1], s13, v148
	global_load_dword v124, v[150:151], off
	global_load_dword v126, v[152:153], off
	v_addc_co_u32_e64 v155, s[0:1], -1, v149, s[0:1]
	global_load_dword v130, v[148:149], off
	global_load_dword v128, v[154:155], off
	v_lshl_add_u64 v[148:149], v[148:149], 0, s[2:3]
	ds_read_b128 v[32:35], v31
	ds_read_b128 v[36:39], v31 offset:4096
	ds_read_b128 v[40:43], v31 offset:8192
	ds_read_b128 v[44:47], v31 offset:12288
	ds_read_b128 v[48:51], v31 offset:16384
	ds_read_b128 v[52:55], v31 offset:20480
	ds_read_b128 v[56:59], v31 offset:24576
	ds_read_b128 v[60:63], v31 offset:28672
	ds_read_b128 v[64:67], v31 offset:32768
	ds_read_b128 v[68:71], v31 offset:36864
	ds_read_b128 v[72:75], v31 offset:40960
	ds_read_b128 v[76:79], v31 offset:45056
	ds_read_b128 v[80:83], v31 offset:49152
	ds_read_b128 v[84:87], v31 offset:53248
	ds_read_b128 v[88:91], v31 offset:57344
	ds_read_b128 v[92:95], v31 offset:61440
	v_add_u32_e32 v31, 0x10000, v31
	ds_read_b128 v[96:99], v31
	s_waitcnt lgkmcnt(14)
	v_mov_b32_e32 v108, v32
	v_mov_b32_e32 v109, v36
	v_mov_b32_e32 v110, v40
	s_waitcnt lgkmcnt(13)
	v_mov_b32_e32 v111, v44
	s_waitcnt lgkmcnt(12)
	v_mov_b32_e32 v112, v48
	s_waitcnt lgkmcnt(11)
	v_mov_b32_e32 v113, v52
	s_waitcnt lgkmcnt(10)
	v_mov_b32_e32 v114, v56
	s_waitcnt lgkmcnt(9)
	v_mov_b32_e32 v115, v60
	s_waitcnt lgkmcnt(8)
	v_mov_b32_e32 v116, v64
	s_waitcnt lgkmcnt(7)
	v_mov_b32_e32 v117, v68
	s_waitcnt lgkmcnt(6)
	v_mov_b32_e32 v118, v72
	s_waitcnt lgkmcnt(5)
	v_mov_b32_e32 v119, v76
	s_waitcnt lgkmcnt(4)
	v_mov_b32_e32 v120, v80
	s_waitcnt lgkmcnt(3)
	v_mov_b32_e32 v121, v84
	s_waitcnt lgkmcnt(2)
	v_mov_b32_e32 v122, v88
	s_waitcnt lgkmcnt(1)
	v_mov_b32_e32 v123, v92
	v_mov_b32_e32 v36, v33
	v_mov_b32_e32 v44, v41
	v_mov_b32_e32 v52, v49
	v_mov_b32_e32 v60, v57
	v_mov_b32_e32 v68, v65
	v_mov_b32_e32 v76, v73
	v_mov_b32_e32 v84, v81
	v_mov_b32_e32 v92, v89
	v_mov_b32_e32 v32, v34
	v_mov_b32_e32 v33, v38
	v_mov_b32_e32 v40, v42
	v_mov_b32_e32 v41, v46
	v_mov_b32_e32 v48, v50
	v_mov_b32_e32 v49, v54
	v_mov_b32_e32 v56, v58
	v_mov_b32_e32 v57, v62
	v_mov_b32_e32 v64, v66
	v_mov_b32_e32 v65, v70
	v_mov_b32_e32 v72, v74
	v_mov_b32_e32 v73, v78
	v_mov_b32_e32 v38, v35
	v_mov_b32_e32 v34, v82
	v_mov_b32_e32 v35, v86
	v_mov_b32_e32 v80, v90
	v_mov_b32_e32 v81, v94
	v_mov_b32_e32 v46, v43
	v_mov_b32_e32 v54, v51
	v_mov_b32_e32 v62, v59
	v_mov_b32_e32 v70, v67
	v_mov_b32_e32 v78, v75
	v_mov_b32_e32 v86, v83
	v_mov_b32_e32 v94, v91
	s_waitcnt vmcnt(12)
	v_pk_fma_f32 v[12:13], v[132:133], v[108:109], v[12:13] op_sel_hi:[0,1,1]
	v_pk_fma_f32 v[14:15], v[132:133], v[110:111], v[14:15] op_sel_hi:[0,1,1]
	v_pk_fma_f32 v[16:17], v[132:133], v[112:113], v[16:17] op_sel_hi:[0,1,1]
	v_pk_fma_f32 v[18:19], v[132:133], v[114:115], v[18:19] op_sel_hi:[0,1,1]
	v_pk_fma_f32 v[20:21], v[132:133], v[116:117], v[20:21] op_sel_hi:[0,1,1]
	v_pk_fma_f32 v[22:23], v[132:133], v[118:119], v[22:23] op_sel_hi:[0,1,1]
	v_pk_fma_f32 v[24:25], v[132:133], v[120:121], v[24:25] op_sel_hi:[0,1,1]
	v_pk_fma_f32 v[26:27], v[132:133], v[122:123], v[26:27] op_sel_hi:[0,1,1]
	s_waitcnt lgkmcnt(0)
	v_fmac_f32_e32 v30, v132, v96
	v_pk_fma_f32 v[12:13], v[134:135], v[36:37], v[12:13] op_sel_hi:[0,1,1]
	v_pk_fma_f32 v[14:15], v[134:135], v[44:45], v[14:15] op_sel_hi:[0,1,1]
	v_pk_fma_f32 v[16:17], v[134:135], v[52:53], v[16:17] op_sel_hi:[0,1,1]
	v_pk_fma_f32 v[18:19], v[134:135], v[60:61], v[18:19] op_sel_hi:[0,1,1]
	v_pk_fma_f32 v[20:21], v[134:135], v[68:69], v[20:21] op_sel_hi:[0,1,1]
	v_pk_fma_f32 v[22:23], v[134:135], v[76:77], v[22:23] op_sel_hi:[0,1,1]
	v_pk_fma_f32 v[24:25], v[134:135], v[84:85], v[24:25] op_sel_hi:[0,1,1]
	v_pk_fma_f32 v[26:27], v[134:135], v[92:93], v[26:27] op_sel_hi:[0,1,1]
	v_fmac_f32_e32 v30, v134, v97
	v_pk_fma_f32 v[12:13], v[136:137], v[32:33], v[12:13] op_sel_hi:[0,1,1]
	v_pk_fma_f32 v[14:15], v[136:137], v[40:41], v[14:15] op_sel_hi:[0,1,1]
	v_pk_fma_f32 v[16:17], v[136:137], v[48:49], v[16:17] op_sel_hi:[0,1,1]
	v_pk_fma_f32 v[18:19], v[136:137], v[56:57], v[18:19] op_sel_hi:[0,1,1]
	v_pk_fma_f32 v[20:21], v[136:137], v[64:65], v[20:21] op_sel_hi:[0,1,1]
	v_pk_fma_f32 v[22:23], v[136:137], v[72:73], v[22:23] op_sel_hi:[0,1,1]
	v_pk_fma_f32 v[24:25], v[136:137], v[34:35], v[24:25] op_sel_hi:[0,1,1]
	v_pk_fma_f32 v[26:27], v[136:137], v[80:81], v[26:27] op_sel_hi:[0,1,1]
	v_fmac_f32_e32 v30, v136, v98
	v_pk_fma_f32 v[12:13], v[138:139], v[38:39], v[12:13] op_sel_hi:[0,1,1]
	v_pk_fma_f32 v[14:15], v[138:139], v[46:47], v[14:15] op_sel_hi:[0,1,1]
	v_pk_fma_f32 v[16:17], v[138:139], v[54:55], v[16:17] op_sel_hi:[0,1,1]
	v_pk_fma_f32 v[18:19], v[138:139], v[62:63], v[18:19] op_sel_hi:[0,1,1]
	v_pk_fma_f32 v[20:21], v[138:139], v[70:71], v[20:21] op_sel_hi:[0,1,1]
	v_pk_fma_f32 v[22:23], v[138:139], v[78:79], v[22:23] op_sel_hi:[0,1,1]
	v_pk_fma_f32 v[24:25], v[138:139], v[86:87], v[24:25] op_sel_hi:[0,1,1]
	v_pk_fma_f32 v[26:27], v[138:139], v[94:95], v[26:27] op_sel_hi:[0,1,1]
	v_fmac_f32_e32 v30, v138, v99
	v_add_u32_e32 v31, s6, v3
	s_add_i32 s6, s6, 16
	v_add_co_u32_e64 v150, s[0:1], s11, v148
	s_nop 1
	v_addc_co_u32_e64 v151, s[0:1], -1, v149, s[0:1]
	v_add_co_u32_e64 v152, s[0:1], s12, v148
	s_nop 1
	v_addc_co_u32_e64 v153, s[0:1], -1, v149, s[0:1]
	v_add_co_u32_e64 v154, s[0:1], s13, v148
	global_load_dword v132, v[150:151], off
	global_load_dword v134, v[152:153], off
	v_addc_co_u32_e64 v155, s[0:1], -1, v149, s[0:1]
	global_load_dword v138, v[148:149], off
	global_load_dword v136, v[154:155], off
	v_lshl_add_u64 v[148:149], v[148:149], 0, s[2:3]
	ds_read_b128 v[32:35], v31
	ds_read_b128 v[36:39], v31 offset:4096
	ds_read_b128 v[40:43], v31 offset:8192
	ds_read_b128 v[44:47], v31 offset:12288
	ds_read_b128 v[48:51], v31 offset:16384
	ds_read_b128 v[52:55], v31 offset:20480
	ds_read_b128 v[56:59], v31 offset:24576
	ds_read_b128 v[60:63], v31 offset:28672
	ds_read_b128 v[64:67], v31 offset:32768
	ds_read_b128 v[68:71], v31 offset:36864
	ds_read_b128 v[72:75], v31 offset:40960
	ds_read_b128 v[76:79], v31 offset:45056
	ds_read_b128 v[80:83], v31 offset:49152
	ds_read_b128 v[84:87], v31 offset:53248
	ds_read_b128 v[88:91], v31 offset:57344
	ds_read_b128 v[92:95], v31 offset:61440
	v_add_u32_e32 v31, 0x10000, v31
	ds_read_b128 v[96:99], v31
	s_waitcnt lgkmcnt(14)
	v_mov_b32_e32 v108, v32
	v_mov_b32_e32 v109, v36
	v_mov_b32_e32 v110, v40
	s_waitcnt lgkmcnt(13)
	v_mov_b32_e32 v111, v44
	s_waitcnt lgkmcnt(12)
	v_mov_b32_e32 v112, v48
	s_waitcnt lgkmcnt(11)
	v_mov_b32_e32 v113, v52
	s_waitcnt lgkmcnt(10)
	v_mov_b32_e32 v114, v56
	s_waitcnt lgkmcnt(9)
	v_mov_b32_e32 v115, v60
	s_waitcnt lgkmcnt(8)
	v_mov_b32_e32 v116, v64
	s_waitcnt lgkmcnt(7)
	v_mov_b32_e32 v117, v68
	s_waitcnt lgkmcnt(6)
	v_mov_b32_e32 v118, v72
	s_waitcnt lgkmcnt(5)
	v_mov_b32_e32 v119, v76
	s_waitcnt lgkmcnt(4)
	v_mov_b32_e32 v120, v80
	s_waitcnt lgkmcnt(3)
	v_mov_b32_e32 v121, v84
	s_waitcnt lgkmcnt(2)
	v_mov_b32_e32 v122, v88
	s_waitcnt lgkmcnt(1)
	v_mov_b32_e32 v123, v92
	v_mov_b32_e32 v36, v33
	v_mov_b32_e32 v44, v41
	v_mov_b32_e32 v52, v49
	v_mov_b32_e32 v60, v57
	v_mov_b32_e32 v68, v65
	v_mov_b32_e32 v76, v73
	v_mov_b32_e32 v84, v81
	v_mov_b32_e32 v92, v89
	v_mov_b32_e32 v32, v34
	v_mov_b32_e32 v33, v38
	v_mov_b32_e32 v40, v42
	v_mov_b32_e32 v41, v46
	v_mov_b32_e32 v48, v50
	v_mov_b32_e32 v49, v54
	v_mov_b32_e32 v56, v58
	v_mov_b32_e32 v57, v62
	v_mov_b32_e32 v64, v66
	v_mov_b32_e32 v65, v70
	v_mov_b32_e32 v72, v74
	v_mov_b32_e32 v73, v78
	v_mov_b32_e32 v38, v35
	v_mov_b32_e32 v34, v82
	v_mov_b32_e32 v35, v86
	v_mov_b32_e32 v80, v90
	v_mov_b32_e32 v81, v94
	v_mov_b32_e32 v46, v43
	v_mov_b32_e32 v54, v51
	v_mov_b32_e32 v62, v59
	v_mov_b32_e32 v70, v67
	v_mov_b32_e32 v78, v75
	v_mov_b32_e32 v86, v83
	v_mov_b32_e32 v94, v91
	s_waitcnt vmcnt(12)
	v_pk_fma_f32 v[12:13], v[140:141], v[108:109], v[12:13] op_sel_hi:[0,1,1]
	v_pk_fma_f32 v[14:15], v[140:141], v[110:111], v[14:15] op_sel_hi:[0,1,1]
	v_pk_fma_f32 v[16:17], v[140:141], v[112:113], v[16:17] op_sel_hi:[0,1,1]
	v_pk_fma_f32 v[18:19], v[140:141], v[114:115], v[18:19] op_sel_hi:[0,1,1]
	v_pk_fma_f32 v[20:21], v[140:141], v[116:117], v[20:21] op_sel_hi:[0,1,1]
	v_pk_fma_f32 v[22:23], v[140:141], v[118:119], v[22:23] op_sel_hi:[0,1,1]
	v_pk_fma_f32 v[24:25], v[140:141], v[120:121], v[24:25] op_sel_hi:[0,1,1]
	v_pk_fma_f32 v[26:27], v[140:141], v[122:123], v[26:27] op_sel_hi:[0,1,1]
	s_waitcnt lgkmcnt(0)
	v_fmac_f32_e32 v30, v140, v96
	v_pk_fma_f32 v[12:13], v[142:143], v[36:37], v[12:13] op_sel_hi:[0,1,1]
	v_pk_fma_f32 v[14:15], v[142:143], v[44:45], v[14:15] op_sel_hi:[0,1,1]
	v_pk_fma_f32 v[16:17], v[142:143], v[52:53], v[16:17] op_sel_hi:[0,1,1]
	v_pk_fma_f32 v[18:19], v[142:143], v[60:61], v[18:19] op_sel_hi:[0,1,1]
	v_pk_fma_f32 v[20:21], v[142:143], v[68:69], v[20:21] op_sel_hi:[0,1,1]
	v_pk_fma_f32 v[22:23], v[142:143], v[76:77], v[22:23] op_sel_hi:[0,1,1]
	v_pk_fma_f32 v[24:25], v[142:143], v[84:85], v[24:25] op_sel_hi:[0,1,1]
	v_pk_fma_f32 v[26:27], v[142:143], v[92:93], v[26:27] op_sel_hi:[0,1,1]
	v_fmac_f32_e32 v30, v142, v97
	v_pk_fma_f32 v[12:13], v[144:145], v[32:33], v[12:13] op_sel_hi:[0,1,1]
	v_pk_fma_f32 v[14:15], v[144:145], v[40:41], v[14:15] op_sel_hi:[0,1,1]
	v_pk_fma_f32 v[16:17], v[144:145], v[48:49], v[16:17] op_sel_hi:[0,1,1]
	v_pk_fma_f32 v[18:19], v[144:145], v[56:57], v[18:19] op_sel_hi:[0,1,1]
	v_pk_fma_f32 v[20:21], v[144:145], v[64:65], v[20:21] op_sel_hi:[0,1,1]
	v_pk_fma_f32 v[22:23], v[144:145], v[72:73], v[22:23] op_sel_hi:[0,1,1]
	v_pk_fma_f32 v[24:25], v[144:145], v[34:35], v[24:25] op_sel_hi:[0,1,1]
	v_pk_fma_f32 v[26:27], v[144:145], v[80:81], v[26:27] op_sel_hi:[0,1,1]
	v_fmac_f32_e32 v30, v144, v98
	v_pk_fma_f32 v[12:13], v[146:147], v[38:39], v[12:13] op_sel_hi:[0,1,1]
	v_pk_fma_f32 v[14:15], v[146:147], v[46:47], v[14:15] op_sel_hi:[0,1,1]
	v_pk_fma_f32 v[16:17], v[146:147], v[54:55], v[16:17] op_sel_hi:[0,1,1]
	v_pk_fma_f32 v[18:19], v[146:147], v[62:63], v[18:19] op_sel_hi:[0,1,1]
	v_pk_fma_f32 v[20:21], v[146:147], v[70:71], v[20:21] op_sel_hi:[0,1,1]
	v_pk_fma_f32 v[22:23], v[146:147], v[78:79], v[22:23] op_sel_hi:[0,1,1]
	v_pk_fma_f32 v[24:25], v[146:147], v[86:87], v[24:25] op_sel_hi:[0,1,1]
	v_pk_fma_f32 v[26:27], v[146:147], v[94:95], v[26:27] op_sel_hi:[0,1,1]
	v_fmac_f32_e32 v30, v146, v99
	s_cmpk_eq_i32 s6, 0x1c0
	s_cbranch_scc0 .Lmodp_loop
	v_add_u32_e32 v31, s6, v3
	s_add_i32 s6, s6, 16
	v_add_co_u32_e64 v150, s[0:1], s11, v148
	s_nop 1
	v_addc_co_u32_e64 v151, s[0:1], -1, v149, s[0:1]
	v_add_co_u32_e64 v152, s[0:1], s12, v148
	s_nop 1
	v_addc_co_u32_e64 v153, s[0:1], -1, v149, s[0:1]
	v_add_co_u32_e64 v154, s[0:1], s13, v148
	global_load_dword v140, v[150:151], off
	global_load_dword v142, v[152:153], off
	v_addc_co_u32_e64 v155, s[0:1], -1, v149, s[0:1]
	global_load_dword v146, v[148:149], off
	global_load_dword v144, v[154:155], off
	v_lshl_add_u64 v[148:149], v[148:149], 0, s[2:3]
	ds_read_b128 v[32:35], v31
	ds_read_b128 v[36:39], v31 offset:4096
	ds_read_b128 v[40:43], v31 offset:8192
	ds_read_b128 v[44:47], v31 offset:12288
	ds_read_b128 v[48:51], v31 offset:16384
	ds_read_b128 v[52:55], v31 offset:20480
	ds_read_b128 v[56:59], v31 offset:24576
	ds_read_b128 v[60:63], v31 offset:28672
	ds_read_b128 v[64:67], v31 offset:32768
	ds_read_b128 v[68:71], v31 offset:36864
	ds_read_b128 v[72:75], v31 offset:40960
	ds_read_b128 v[76:79], v31 offset:45056
	ds_read_b128 v[80:83], v31 offset:49152
	ds_read_b128 v[84:87], v31 offset:53248
	ds_read_b128 v[88:91], v31 offset:57344
	ds_read_b128 v[92:95], v31 offset:61440
	v_add_u32_e32 v31, 0x10000, v31
	ds_read_b128 v[96:99], v31
	s_waitcnt lgkmcnt(14)
	v_mov_b32_e32 v108, v32
	v_mov_b32_e32 v109, v36
	v_mov_b32_e32 v110, v40
	s_waitcnt lgkmcnt(13)
	v_mov_b32_e32 v111, v44
	s_waitcnt lgkmcnt(12)
	v_mov_b32_e32 v112, v48
	s_waitcnt lgkmcnt(11)
	v_mov_b32_e32 v113, v52
	s_waitcnt lgkmcnt(10)
	v_mov_b32_e32 v114, v56
	s_waitcnt lgkmcnt(9)
	v_mov_b32_e32 v115, v60
	s_waitcnt lgkmcnt(8)
	v_mov_b32_e32 v116, v64
	s_waitcnt lgkmcnt(7)
	v_mov_b32_e32 v117, v68
	s_waitcnt lgkmcnt(6)
	v_mov_b32_e32 v118, v72
	s_waitcnt lgkmcnt(5)
	v_mov_b32_e32 v119, v76
	s_waitcnt lgkmcnt(4)
	v_mov_b32_e32 v120, v80
	s_waitcnt lgkmcnt(3)
	v_mov_b32_e32 v121, v84
	s_waitcnt lgkmcnt(2)
	v_mov_b32_e32 v122, v88
	s_waitcnt lgkmcnt(1)
	v_mov_b32_e32 v123, v92
	v_mov_b32_e32 v36, v33
	v_mov_b32_e32 v44, v41
	v_mov_b32_e32 v52, v49
	v_mov_b32_e32 v60, v57
	v_mov_b32_e32 v68, v65
	v_mov_b32_e32 v76, v73
	v_mov_b32_e32 v84, v81
	v_mov_b32_e32 v92, v89
	v_mov_b32_e32 v32, v34
	v_mov_b32_e32 v33, v38
	v_mov_b32_e32 v40, v42
	v_mov_b32_e32 v41, v46
	v_mov_b32_e32 v48, v50
	v_mov_b32_e32 v49, v54
	v_mov_b32_e32 v56, v58
	v_mov_b32_e32 v57, v62
	v_mov_b32_e32 v64, v66
	v_mov_b32_e32 v65, v70
	v_mov_b32_e32 v72, v74
	v_mov_b32_e32 v73, v78
	v_mov_b32_e32 v38, v35
	v_mov_b32_e32 v34, v82
	v_mov_b32_e32 v35, v86
	v_mov_b32_e32 v80, v90
	v_mov_b32_e32 v81, v94
	v_mov_b32_e32 v46, v43
	v_mov_b32_e32 v54, v51
	v_mov_b32_e32 v62, v59
	v_mov_b32_e32 v70, v67
	v_mov_b32_e32 v78, v75
	v_mov_b32_e32 v86, v83
	v_mov_b32_e32 v94, v91
	s_waitcnt vmcnt(12)
	v_pk_fma_f32 v[12:13], v[100:101], v[108:109], v[12:13] op_sel_hi:[0,1,1]
	v_pk_fma_f32 v[14:15], v[100:101], v[110:111], v[14:15] op_sel_hi:[0,1,1]
	v_pk_fma_f32 v[16:17], v[100:101], v[112:113], v[16:17] op_sel_hi:[0,1,1]
	v_pk_fma_f32 v[18:19], v[100:101], v[114:115], v[18:19] op_sel_hi:[0,1,1]
	v_pk_fma_f32 v[20:21], v[100:101], v[116:117], v[20:21] op_sel_hi:[0,1,1]
	v_pk_fma_f32 v[22:23], v[100:101], v[118:119], v[22:23] op_sel_hi:[0,1,1]
	v_pk_fma_f32 v[24:25], v[100:101], v[120:121], v[24:25] op_sel_hi:[0,1,1]
	v_pk_fma_f32 v[26:27], v[100:101], v[122:123], v[26:27] op_sel_hi:[0,1,1]
	s_waitcnt lgkmcnt(0)
	v_fmac_f32_e32 v30, v100, v96
	v_pk_fma_f32 v[12:13], v[102:103], v[36:37], v[12:13] op_sel_hi:[0,1,1]
	v_pk_fma_f32 v[14:15], v[102:103], v[44:45], v[14:15] op_sel_hi:[0,1,1]
	v_pk_fma_f32 v[16:17], v[102:103], v[52:53], v[16:17] op_sel_hi:[0,1,1]
	v_pk_fma_f32 v[18:19], v[102:103], v[60:61], v[18:19] op_sel_hi:[0,1,1]
	v_pk_fma_f32 v[20:21], v[102:103], v[68:69], v[20:21] op_sel_hi:[0,1,1]
	v_pk_fma_f32 v[22:23], v[102:103], v[76:77], v[22:23] op_sel_hi:[0,1,1]
	v_pk_fma_f32 v[24:25], v[102:103], v[84:85], v[24:25] op_sel_hi:[0,1,1]
	v_pk_fma_f32 v[26:27], v[102:103], v[92:93], v[26:27] op_sel_hi:[0,1,1]
	v_fmac_f32_e32 v30, v102, v97
	v_pk_fma_f32 v[12:13], v[104:105], v[32:33], v[12:13] op_sel_hi:[0,1,1]
	v_pk_fma_f32 v[14:15], v[104:105], v[40:41], v[14:15] op_sel_hi:[0,1,1]
	v_pk_fma_f32 v[16:17], v[104:105], v[48:49], v[16:17] op_sel_hi:[0,1,1]
	v_pk_fma_f32 v[18:19], v[104:105], v[56:57], v[18:19] op_sel_hi:[0,1,1]
	v_pk_fma_f32 v[20:21], v[104:105], v[64:65], v[20:21] op_sel_hi:[0,1,1]
	v_pk_fma_f32 v[22:23], v[104:105], v[72:73], v[22:23] op_sel_hi:[0,1,1]
	v_pk_fma_f32 v[24:25], v[104:105], v[34:35], v[24:25] op_sel_hi:[0,1,1]
	v_pk_fma_f32 v[26:27], v[104:105], v[80:81], v[26:27] op_sel_hi:[0,1,1]
	v_fmac_f32_e32 v30, v104, v98
	v_pk_fma_f32 v[12:13], v[106:107], v[38:39], v[12:13] op_sel_hi:[0,1,1]
	v_pk_fma_f32 v[14:15], v[106:107], v[46:47], v[14:15] op_sel_hi:[0,1,1]
	v_pk_fma_f32 v[16:17], v[106:107], v[54:55], v[16:17] op_sel_hi:[0,1,1]
	v_pk_fma_f32 v[18:19], v[106:107], v[62:63], v[18:19] op_sel_hi:[0,1,1]
	v_pk_fma_f32 v[20:21], v[106:107], v[70:71], v[20:21] op_sel_hi:[0,1,1]
	v_pk_fma_f32 v[22:23], v[106:107], v[78:79], v[22:23] op_sel_hi:[0,1,1]
	v_pk_fma_f32 v[24:25], v[106:107], v[86:87], v[24:25] op_sel_hi:[0,1,1]
	v_pk_fma_f32 v[26:27], v[106:107], v[94:95], v[26:27] op_sel_hi:[0,1,1]
	v_fmac_f32_e32 v30, v106, v99
	v_add_u32_e32 v31, s6, v3
	s_add_i32 s6, s6, 16
	ds_read_b128 v[32:35], v31
	ds_read_b128 v[36:39], v31 offset:4096
	ds_read_b128 v[40:43], v31 offset:8192
	ds_read_b128 v[44:47], v31 offset:12288
	ds_read_b128 v[48:51], v31 offset:16384
	ds_read_b128 v[52:55], v31 offset:20480
	ds_read_b128 v[56:59], v31 offset:24576
	ds_read_b128 v[60:63], v31 offset:28672
	ds_read_b128 v[64:67], v31 offset:32768
	ds_read_b128 v[68:71], v31 offset:36864
	ds_read_b128 v[72:75], v31 offset:40960
	ds_read_b128 v[76:79], v31 offset:45056
	ds_read_b128 v[80:83], v31 offset:49152
	ds_read_b128 v[84:87], v31 offset:53248
	ds_read_b128 v[88:91], v31 offset:57344
	ds_read_b128 v[92:95], v31 offset:61440
	v_add_u32_e32 v31, 0x10000, v31
	ds_read_b128 v[96:99], v31
	s_waitcnt lgkmcnt(14)
	v_mov_b32_e32 v108, v32
	v_mov_b32_e32 v109, v36
	v_mov_b32_e32 v110, v40
	s_waitcnt lgkmcnt(13)
	v_mov_b32_e32 v111, v44
	s_waitcnt lgkmcnt(12)
	v_mov_b32_e32 v112, v48
	s_waitcnt lgkmcnt(11)
	v_mov_b32_e32 v113, v52
	s_waitcnt lgkmcnt(10)
	v_mov_b32_e32 v114, v56
	s_waitcnt lgkmcnt(9)
	v_mov_b32_e32 v115, v60
	s_waitcnt lgkmcnt(8)
	v_mov_b32_e32 v116, v64
	s_waitcnt lgkmcnt(7)
	v_mov_b32_e32 v117, v68
	s_waitcnt lgkmcnt(6)
	v_mov_b32_e32 v118, v72
	s_waitcnt lgkmcnt(5)
	v_mov_b32_e32 v119, v76
	s_waitcnt lgkmcnt(4)
	v_mov_b32_e32 v120, v80
	s_waitcnt lgkmcnt(3)
	v_mov_b32_e32 v121, v84
	s_waitcnt lgkmcnt(2)
	v_mov_b32_e32 v122, v88
	s_waitcnt lgkmcnt(1)
	v_mov_b32_e32 v123, v92
	v_mov_b32_e32 v36, v33
	v_mov_b32_e32 v44, v41
	v_mov_b32_e32 v52, v49
	v_mov_b32_e32 v60, v57
	v_mov_b32_e32 v68, v65
	v_mov_b32_e32 v76, v73
	v_mov_b32_e32 v84, v81
	v_mov_b32_e32 v92, v89
	v_mov_b32_e32 v32, v34
	v_mov_b32_e32 v33, v38
	v_mov_b32_e32 v40, v42
	v_mov_b32_e32 v41, v46
	v_mov_b32_e32 v48, v50
	v_mov_b32_e32 v49, v54
	v_mov_b32_e32 v56, v58
	v_mov_b32_e32 v57, v62
	v_mov_b32_e32 v64, v66
	v_mov_b32_e32 v65, v70
	v_mov_b32_e32 v72, v74
	v_mov_b32_e32 v73, v78
	v_mov_b32_e32 v38, v35
	v_mov_b32_e32 v34, v82
	v_mov_b32_e32 v35, v86
	v_mov_b32_e32 v80, v90
	v_mov_b32_e32 v81, v94
	v_mov_b32_e32 v46, v43
	v_mov_b32_e32 v54, v51
	v_mov_b32_e32 v62, v59
	v_mov_b32_e32 v70, v67
	v_mov_b32_e32 v78, v75
	v_mov_b32_e32 v86, v83
	v_mov_b32_e32 v94, v91
	s_waitcnt vmcnt(8)
	v_pk_fma_f32 v[12:13], v[124:125], v[108:109], v[12:13] op_sel_hi:[0,1,1]
	v_pk_fma_f32 v[14:15], v[124:125], v[110:111], v[14:15] op_sel_hi:[0,1,1]
	v_pk_fma_f32 v[16:17], v[124:125], v[112:113], v[16:17] op_sel_hi:[0,1,1]
	v_pk_fma_f32 v[18:19], v[124:125], v[114:115], v[18:19] op_sel_hi:[0,1,1]
	v_pk_fma_f32 v[20:21], v[124:125], v[116:117], v[20:21] op_sel_hi:[0,1,1]
	v_pk_fma_f32 v[22:23], v[124:125], v[118:119], v[22:23] op_sel_hi:[0,1,1]
	v_pk_fma_f32 v[24:25], v[124:125], v[120:121], v[24:25] op_sel_hi:[0,1,1]
	v_pk_fma_f32 v[26:27], v[124:125], v[122:123], v[26:27] op_sel_hi:[0,1,1]
	s_waitcnt lgkmcnt(0)
	v_fmac_f32_e32 v30, v124, v96
	v_pk_fma_f32 v[12:13], v[126:127], v[36:37], v[12:13] op_sel_hi:[0,1,1]
	v_pk_fma_f32 v[14:15], v[126:127], v[44:45], v[14:15] op_sel_hi:[0,1,1]
	v_pk_fma_f32 v[16:17], v[126:127], v[52:53], v[16:17] op_sel_hi:[0,1,1]
	v_pk_fma_f32 v[18:19], v[126:127], v[60:61], v[18:19] op_sel_hi:[0,1,1]
	v_pk_fma_f32 v[20:21], v[126:127], v[68:69], v[20:21] op_sel_hi:[0,1,1]
	v_pk_fma_f32 v[22:23], v[126:127], v[76:77], v[22:23] op_sel_hi:[0,1,1]
	v_pk_fma_f32 v[24:25], v[126:127], v[84:85], v[24:25] op_sel_hi:[0,1,1]
	v_pk_fma_f32 v[26:27], v[126:127], v[92:93], v[26:27] op_sel_hi:[0,1,1]
	v_fmac_f32_e32 v30, v126, v97
	v_pk_fma_f32 v[12:13], v[128:129], v[32:33], v[12:13] op_sel_hi:[0,1,1]
	v_pk_fma_f32 v[14:15], v[128:129], v[40:41], v[14:15] op_sel_hi:[0,1,1]
	v_pk_fma_f32 v[16:17], v[128:129], v[48:49], v[16:17] op_sel_hi:[0,1,1]
	v_pk_fma_f32 v[18:19], v[128:129], v[56:57], v[18:19] op_sel_hi:[0,1,1]
	v_pk_fma_f32 v[20:21], v[128:129], v[64:65], v[20:21] op_sel_hi:[0,1,1]
	v_pk_fma_f32 v[22:23], v[128:129], v[72:73], v[22:23] op_sel_hi:[0,1,1]
	v_pk_fma_f32 v[24:25], v[128:129], v[34:35], v[24:25] op_sel_hi:[0,1,1]
	v_pk_fma_f32 v[26:27], v[128:129], v[80:81], v[26:27] op_sel_hi:[0,1,1]
	v_fmac_f32_e32 v30, v128, v98
	v_pk_fma_f32 v[12:13], v[130:131], v[38:39], v[12:13] op_sel_hi:[0,1,1]
	v_pk_fma_f32 v[14:15], v[130:131], v[46:47], v[14:15] op_sel_hi:[0,1,1]
	v_pk_fma_f32 v[16:17], v[130:131], v[54:55], v[16:17] op_sel_hi:[0,1,1]
	v_pk_fma_f32 v[18:19], v[130:131], v[62:63], v[18:19] op_sel_hi:[0,1,1]
	v_pk_fma_f32 v[20:21], v[130:131], v[70:71], v[20:21] op_sel_hi:[0,1,1]
	v_pk_fma_f32 v[22:23], v[130:131], v[78:79], v[22:23] op_sel_hi:[0,1,1]
	v_pk_fma_f32 v[24:25], v[130:131], v[86:87], v[24:25] op_sel_hi:[0,1,1]
	v_pk_fma_f32 v[26:27], v[130:131], v[94:95], v[26:27] op_sel_hi:[0,1,1]
	v_fmac_f32_e32 v30, v130, v99
	v_add_u32_e32 v31, s6, v3
	s_add_i32 s6, s6, 16
	ds_read_b128 v[32:35], v31
	ds_read_b128 v[36:39], v31 offset:4096
	ds_read_b128 v[40:43], v31 offset:8192
	ds_read_b128 v[44:47], v31 offset:12288
	ds_read_b128 v[48:51], v31 offset:16384
	ds_read_b128 v[52:55], v31 offset:20480
	ds_read_b128 v[56:59], v31 offset:24576
	ds_read_b128 v[60:63], v31 offset:28672
	ds_read_b128 v[64:67], v31 offset:32768
	ds_read_b128 v[68:71], v31 offset:36864
	ds_read_b128 v[72:75], v31 offset:40960
	ds_read_b128 v[76:79], v31 offset:45056
	ds_read_b128 v[80:83], v31 offset:49152
	ds_read_b128 v[84:87], v31 offset:53248
	ds_read_b128 v[88:91], v31 offset:57344
	ds_read_b128 v[92:95], v31 offset:61440
	v_add_u32_e32 v31, 0x10000, v31
	ds_read_b128 v[96:99], v31
	s_waitcnt lgkmcnt(14)
	v_mov_b32_e32 v108, v32
	v_mov_b32_e32 v109, v36
	v_mov_b32_e32 v110, v40
	s_waitcnt lgkmcnt(13)
	v_mov_b32_e32 v111, v44
	s_waitcnt lgkmcnt(12)
	v_mov_b32_e32 v112, v48
	s_waitcnt lgkmcnt(11)
	v_mov_b32_e32 v113, v52
	s_waitcnt lgkmcnt(10)
	v_mov_b32_e32 v114, v56
	s_waitcnt lgkmcnt(9)
	v_mov_b32_e32 v115, v60
	s_waitcnt lgkmcnt(8)
	v_mov_b32_e32 v116, v64
	s_waitcnt lgkmcnt(7)
	v_mov_b32_e32 v117, v68
	s_waitcnt lgkmcnt(6)
	v_mov_b32_e32 v118, v72
	s_waitcnt lgkmcnt(5)
	v_mov_b32_e32 v119, v76
	s_waitcnt lgkmcnt(4)
	v_mov_b32_e32 v120, v80
	s_waitcnt lgkmcnt(3)
	v_mov_b32_e32 v121, v84
	s_waitcnt lgkmcnt(2)
	v_mov_b32_e32 v122, v88
	s_waitcnt lgkmcnt(1)
	v_mov_b32_e32 v123, v92
	v_mov_b32_e32 v36, v33
	v_mov_b32_e32 v44, v41
	v_mov_b32_e32 v52, v49
	v_mov_b32_e32 v60, v57
	v_mov_b32_e32 v68, v65
	v_mov_b32_e32 v76, v73
	v_mov_b32_e32 v84, v81
	v_mov_b32_e32 v92, v89
	v_mov_b32_e32 v32, v34
	v_mov_b32_e32 v33, v38
	v_mov_b32_e32 v40, v42
	v_mov_b32_e32 v41, v46
	v_mov_b32_e32 v48, v50
	v_mov_b32_e32 v49, v54
	v_mov_b32_e32 v56, v58
	v_mov_b32_e32 v57, v62
	v_mov_b32_e32 v64, v66
	v_mov_b32_e32 v65, v70
	v_mov_b32_e32 v72, v74
	v_mov_b32_e32 v73, v78
	v_mov_b32_e32 v38, v35
	v_mov_b32_e32 v34, v82
	v_mov_b32_e32 v35, v86
	v_mov_b32_e32 v80, v90
	v_mov_b32_e32 v81, v94
	v_mov_b32_e32 v46, v43
	v_mov_b32_e32 v54, v51
	v_mov_b32_e32 v62, v59
	v_mov_b32_e32 v70, v67
	v_mov_b32_e32 v78, v75
	v_mov_b32_e32 v86, v83
	v_mov_b32_e32 v94, v91
	s_waitcnt vmcnt(4)
	v_pk_fma_f32 v[12:13], v[132:133], v[108:109], v[12:13] op_sel_hi:[0,1,1]
	v_pk_fma_f32 v[14:15], v[132:133], v[110:111], v[14:15] op_sel_hi:[0,1,1]
	v_pk_fma_f32 v[16:17], v[132:133], v[112:113], v[16:17] op_sel_hi:[0,1,1]
	v_pk_fma_f32 v[18:19], v[132:133], v[114:115], v[18:19] op_sel_hi:[0,1,1]
	v_pk_fma_f32 v[20:21], v[132:133], v[116:117], v[20:21] op_sel_hi:[0,1,1]
	v_pk_fma_f32 v[22:23], v[132:133], v[118:119], v[22:23] op_sel_hi:[0,1,1]
	v_pk_fma_f32 v[24:25], v[132:133], v[120:121], v[24:25] op_sel_hi:[0,1,1]
	v_pk_fma_f32 v[26:27], v[132:133], v[122:123], v[26:27] op_sel_hi:[0,1,1]
	s_waitcnt lgkmcnt(0)
	v_fmac_f32_e32 v30, v132, v96
	v_pk_fma_f32 v[12:13], v[134:135], v[36:37], v[12:13] op_sel_hi:[0,1,1]
	v_pk_fma_f32 v[14:15], v[134:135], v[44:45], v[14:15] op_sel_hi:[0,1,1]
	v_pk_fma_f32 v[16:17], v[134:135], v[52:53], v[16:17] op_sel_hi:[0,1,1]
	v_pk_fma_f32 v[18:19], v[134:135], v[60:61], v[18:19] op_sel_hi:[0,1,1]
	v_pk_fma_f32 v[20:21], v[134:135], v[68:69], v[20:21] op_sel_hi:[0,1,1]
	v_pk_fma_f32 v[22:23], v[134:135], v[76:77], v[22:23] op_sel_hi:[0,1,1]
	v_pk_fma_f32 v[24:25], v[134:135], v[84:85], v[24:25] op_sel_hi:[0,1,1]
	v_pk_fma_f32 v[26:27], v[134:135], v[92:93], v[26:27] op_sel_hi:[0,1,1]
	v_fmac_f32_e32 v30, v134, v97
	v_pk_fma_f32 v[12:13], v[136:137], v[32:33], v[12:13] op_sel_hi:[0,1,1]
	v_pk_fma_f32 v[14:15], v[136:137], v[40:41], v[14:15] op_sel_hi:[0,1,1]
	v_pk_fma_f32 v[16:17], v[136:137], v[48:49], v[16:17] op_sel_hi:[0,1,1]
	v_pk_fma_f32 v[18:19], v[136:137], v[56:57], v[18:19] op_sel_hi:[0,1,1]
	v_pk_fma_f32 v[20:21], v[136:137], v[64:65], v[20:21] op_sel_hi:[0,1,1]
	v_pk_fma_f32 v[22:23], v[136:137], v[72:73], v[22:23] op_sel_hi:[0,1,1]
	v_pk_fma_f32 v[24:25], v[136:137], v[34:35], v[24:25] op_sel_hi:[0,1,1]
	v_pk_fma_f32 v[26:27], v[136:137], v[80:81], v[26:27] op_sel_hi:[0,1,1]
	v_fmac_f32_e32 v30, v136, v98
	v_pk_fma_f32 v[12:13], v[138:139], v[38:39], v[12:13] op_sel_hi:[0,1,1]
	v_pk_fma_f32 v[14:15], v[138:139], v[46:47], v[14:15] op_sel_hi:[0,1,1]
	v_pk_fma_f32 v[16:17], v[138:139], v[54:55], v[16:17] op_sel_hi:[0,1,1]
	v_pk_fma_f32 v[18:19], v[138:139], v[62:63], v[18:19] op_sel_hi:[0,1,1]
	v_pk_fma_f32 v[20:21], v[138:139], v[70:71], v[20:21] op_sel_hi:[0,1,1]
	v_pk_fma_f32 v[22:23], v[138:139], v[78:79], v[22:23] op_sel_hi:[0,1,1]
	v_pk_fma_f32 v[24:25], v[138:139], v[86:87], v[24:25] op_sel_hi:[0,1,1]
	v_pk_fma_f32 v[26:27], v[138:139], v[94:95], v[26:27] op_sel_hi:[0,1,1]
	v_fmac_f32_e32 v30, v138, v99
	v_add_u32_e32 v31, s6, v3
	s_add_i32 s6, s6, 16
	ds_read_b128 v[32:35], v31
	ds_read_b128 v[36:39], v31 offset:4096
	ds_read_b128 v[40:43], v31 offset:8192
	ds_read_b128 v[44:47], v31 offset:12288
	ds_read_b128 v[48:51], v31 offset:16384
	ds_read_b128 v[52:55], v31 offset:20480
	ds_read_b128 v[56:59], v31 offset:24576
	ds_read_b128 v[60:63], v31 offset:28672
	ds_read_b128 v[64:67], v31 offset:32768
	ds_read_b128 v[68:71], v31 offset:36864
	ds_read_b128 v[72:75], v31 offset:40960
	ds_read_b128 v[76:79], v31 offset:45056
	ds_read_b128 v[80:83], v31 offset:49152
	ds_read_b128 v[84:87], v31 offset:53248
	ds_read_b128 v[88:91], v31 offset:57344
	ds_read_b128 v[92:95], v31 offset:61440
	v_add_u32_e32 v31, 0x10000, v31
	ds_read_b128 v[96:99], v31
	s_waitcnt lgkmcnt(14)
	v_mov_b32_e32 v108, v32
	v_mov_b32_e32 v109, v36
	v_mov_b32_e32 v110, v40
	s_waitcnt lgkmcnt(13)
	v_mov_b32_e32 v111, v44
	s_waitcnt lgkmcnt(12)
	v_mov_b32_e32 v112, v48
	s_waitcnt lgkmcnt(11)
	v_mov_b32_e32 v113, v52
	s_waitcnt lgkmcnt(10)
	v_mov_b32_e32 v114, v56
	s_waitcnt lgkmcnt(9)
	v_mov_b32_e32 v115, v60
	s_waitcnt lgkmcnt(8)
	v_mov_b32_e32 v116, v64
	s_waitcnt lgkmcnt(7)
	v_mov_b32_e32 v117, v68
	s_waitcnt lgkmcnt(6)
	v_mov_b32_e32 v118, v72
	s_waitcnt lgkmcnt(5)
	v_mov_b32_e32 v119, v76
	s_waitcnt lgkmcnt(4)
	v_mov_b32_e32 v120, v80
	s_waitcnt lgkmcnt(3)
	v_mov_b32_e32 v121, v84
	s_waitcnt lgkmcnt(2)
	v_mov_b32_e32 v122, v88
	s_waitcnt lgkmcnt(1)
	v_mov_b32_e32 v123, v92
	v_mov_b32_e32 v36, v33
	v_mov_b32_e32 v44, v41
	v_mov_b32_e32 v52, v49
	v_mov_b32_e32 v60, v57
	v_mov_b32_e32 v68, v65
	v_mov_b32_e32 v76, v73
	v_mov_b32_e32 v84, v81
	v_mov_b32_e32 v92, v89
	v_mov_b32_e32 v32, v34
	v_mov_b32_e32 v33, v38
	v_mov_b32_e32 v40, v42
	v_mov_b32_e32 v41, v46
	v_mov_b32_e32 v48, v50
	v_mov_b32_e32 v49, v54
	v_mov_b32_e32 v56, v58
	v_mov_b32_e32 v57, v62
	v_mov_b32_e32 v64, v66
	v_mov_b32_e32 v65, v70
	v_mov_b32_e32 v72, v74
	v_mov_b32_e32 v73, v78
	v_mov_b32_e32 v38, v35
	v_mov_b32_e32 v34, v82
	v_mov_b32_e32 v35, v86
	v_mov_b32_e32 v80, v90
	v_mov_b32_e32 v81, v94
	v_mov_b32_e32 v46, v43
	v_mov_b32_e32 v54, v51
	v_mov_b32_e32 v62, v59
	v_mov_b32_e32 v70, v67
	v_mov_b32_e32 v78, v75
	v_mov_b32_e32 v86, v83
	v_mov_b32_e32 v94, v91
	s_waitcnt vmcnt(0)
	v_pk_fma_f32 v[12:13], v[140:141], v[108:109], v[12:13] op_sel_hi:[0,1,1]
	v_pk_fma_f32 v[14:15], v[140:141], v[110:111], v[14:15] op_sel_hi:[0,1,1]
	v_pk_fma_f32 v[16:17], v[140:141], v[112:113], v[16:17] op_sel_hi:[0,1,1]
	v_pk_fma_f32 v[18:19], v[140:141], v[114:115], v[18:19] op_sel_hi:[0,1,1]
	v_pk_fma_f32 v[20:21], v[140:141], v[116:117], v[20:21] op_sel_hi:[0,1,1]
	v_pk_fma_f32 v[22:23], v[140:141], v[118:119], v[22:23] op_sel_hi:[0,1,1]
	v_pk_fma_f32 v[24:25], v[140:141], v[120:121], v[24:25] op_sel_hi:[0,1,1]
	v_pk_fma_f32 v[26:27], v[140:141], v[122:123], v[26:27] op_sel_hi:[0,1,1]
	s_waitcnt lgkmcnt(0)
	v_fmac_f32_e32 v30, v140, v96
	v_pk_fma_f32 v[12:13], v[142:143], v[36:37], v[12:13] op_sel_hi:[0,1,1]
	v_pk_fma_f32 v[14:15], v[142:143], v[44:45], v[14:15] op_sel_hi:[0,1,1]
	v_pk_fma_f32 v[16:17], v[142:143], v[52:53], v[16:17] op_sel_hi:[0,1,1]
	v_pk_fma_f32 v[18:19], v[142:143], v[60:61], v[18:19] op_sel_hi:[0,1,1]
	v_pk_fma_f32 v[20:21], v[142:143], v[68:69], v[20:21] op_sel_hi:[0,1,1]
	v_pk_fma_f32 v[22:23], v[142:143], v[76:77], v[22:23] op_sel_hi:[0,1,1]
	v_pk_fma_f32 v[24:25], v[142:143], v[84:85], v[24:25] op_sel_hi:[0,1,1]
	v_pk_fma_f32 v[26:27], v[142:143], v[92:93], v[26:27] op_sel_hi:[0,1,1]
	v_fmac_f32_e32 v30, v142, v97
	v_pk_fma_f32 v[12:13], v[144:145], v[32:33], v[12:13] op_sel_hi:[0,1,1]
	v_pk_fma_f32 v[14:15], v[144:145], v[40:41], v[14:15] op_sel_hi:[0,1,1]
	v_pk_fma_f32 v[16:17], v[144:145], v[48:49], v[16:17] op_sel_hi:[0,1,1]
	v_pk_fma_f32 v[18:19], v[144:145], v[56:57], v[18:19] op_sel_hi:[0,1,1]
	v_pk_fma_f32 v[20:21], v[144:145], v[64:65], v[20:21] op_sel_hi:[0,1,1]
	v_pk_fma_f32 v[22:23], v[144:145], v[72:73], v[22:23] op_sel_hi:[0,1,1]
	v_pk_fma_f32 v[24:25], v[144:145], v[34:35], v[24:25] op_sel_hi:[0,1,1]
	v_pk_fma_f32 v[26:27], v[144:145], v[80:81], v[26:27] op_sel_hi:[0,1,1]
	v_fmac_f32_e32 v30, v144, v98
	v_pk_fma_f32 v[12:13], v[146:147], v[38:39], v[12:13] op_sel_hi:[0,1,1]
	v_pk_fma_f32 v[14:15], v[146:147], v[46:47], v[14:15] op_sel_hi:[0,1,1]
	v_pk_fma_f32 v[16:17], v[146:147], v[54:55], v[16:17] op_sel_hi:[0,1,1]
	v_pk_fma_f32 v[18:19], v[146:147], v[62:63], v[18:19] op_sel_hi:[0,1,1]
	v_pk_fma_f32 v[20:21], v[146:147], v[70:71], v[20:21] op_sel_hi:[0,1,1]
	v_pk_fma_f32 v[22:23], v[146:147], v[78:79], v[22:23] op_sel_hi:[0,1,1]
	v_pk_fma_f32 v[24:25], v[146:147], v[86:87], v[24:25] op_sel_hi:[0,1,1]
	v_pk_fma_f32 v[26:27], v[146:147], v[94:95], v[26:27] op_sel_hi:[0,1,1]
	v_fmac_f32_e32 v30, v146, v99
	ds_write2st64_b32 v4, v12, v13 offset1:1
	ds_write2st64_b32 v4, v14, v15 offset0:2 offset1:3
	ds_write2st64_b32 v4, v16, v17 offset0:4 offset1:5
	ds_write2st64_b32 v4, v18, v19 offset0:6 offset1:7
	ds_write2st64_b32 v4, v20, v21 offset0:8 offset1:9
	ds_write2st64_b32 v4, v22, v23 offset0:10 offset1:11
	ds_write2st64_b32 v4, v24, v25 offset0:12 offset1:13
	ds_write2st64_b32 v4, v26, v27 offset0:14 offset1:15
	ds_write_b32 v4, v30 offset:4096
	s_waitcnt lgkmcnt(0)
	s_barrier
	s_and_saveexec_b64 s[6:7], vcc
	s_cbranch_execz .LBB0_407
	s_mul_i32 s0, s16, 0x1800
	s_add_i32 s0, s0, s4
	v_or_b32_e32 v10, s0, v28
	v_readlane_b32 s40, v252, 17
	v_ashrrev_i32_e32 v11, 31, v10
	v_readlane_b32 s50, v252, 27
	v_readlane_b32 s51, v252, 28
	s_mul_i32 s16, s16, 17
	v_lshl_add_u64 v[12:13], s[4:5], 2, v[6:7]
	v_lshl_add_u64 v[10:11], v[10:11], 2, s[50:51]
	s_mov_b64 s[4:5], 0
	v_mov_b32_e32 v14, v2
	v_readlane_b32 s41, v252, 18
	v_readlane_b32 s42, v252, 19
	v_readlane_b32 s43, v252, 20
	v_readlane_b32 s44, v252, 21
	v_readlane_b32 s45, v252, 22
	v_readlane_b32 s46, v252, 23
	v_readlane_b32 s47, v252, 24
	v_readlane_b32 s48, v252, 25
	v_readlane_b32 s49, v252, 26
	v_readlane_b32 s52, v252, 29
	v_readlane_b32 s53, v252, 30
	v_readlane_b32 s54, v252, 31
	v_readlane_b32 s55, v252, 32
